# v027 plus nt hint on the final residual write-out stores (d_out is not read again inside the kernel)
# speedup vs baseline: 1.0004x; 1.0004x over previous
.LBB0_1152:
	v_ashrrev_i32_e32 v1, 31, v0
	v_lshlrev_b64 v[2:3], 11, v[0:1]
	v_lshl_add_u64 v[2:3], v[18:19], 0, v[2:3]
	global_load_dwordx2 v[4:5], v[2:3], off offset:512
	global_load_dwordx2 v[6:7], v[2:3], off offset:1024
	global_load_dwordx2 v[24:25], v[2:3], off
	global_load_dwordx2 v[26:27], v[2:3], off offset:1536
	v_add_u32_e32 v2, 0xffffe000, v0
	v_ashrrev_i32_e32 v12, 12, v2
	v_lshlrev_b64 v[2:3], 12, v[0:1]
	v_add_u32_e32 v1, 10, v12
	v_cmp_lt_i32_e32 vcc, s11, v0
	v_lshl_add_u64 v[52:53], v[22:23], 0, v[2:3]
	global_load_dwordx4 v[8:11], v[20:21], off
	v_cndmask_b32_e32 v1, 9, v1, vcc
	v_mul_hi_i32_i24_e32 v3, 0x3000, v1
	v_mul_i32_i24_e32 v2, 0x3000, v1
	v_lshl_add_u64 v[2:3], s[0:1], 0, v[2:3]
	v_lshl_add_u64 v[44:45], v[2:3], 0, v[16:17]
	v_add_co_u32_e32 v2, vcc, s12, v44
	global_load_dwordx4 v[12:15], v[52:53], off
	global_load_dwordx4 v[40:43], v[52:53], off offset:1024
	v_addc_co_u32_e32 v3, vcc, 0, v45, vcc
	global_load_dwordx4 v[36:39], v[2:3], off
	s_waitcnt vmcnt(0)
	v_and_b32_e32 v49, 0xffff0000, v4
	v_lshlrev_b32_e32 v47, 16, v4
	v_and_b32_e32 v48, 0xffff0000, v24
	v_lshlrev_b32_e32 v46, 16, v24
	v_and_b32_e32 v59, 0xffff0000, v26
	v_and_b32_e32 v58, 0xffff0000, v6
	v_pk_mul_f32 v[2:3], v[48:49], v[48:49]
	v_lshlrev_b32_e32 v51, 16, v5
	v_lshlrev_b32_e32 v50, 16, v25
	v_and_b32_e32 v55, 0xffff0000, v5
	v_lshlrev_b32_e32 v57, 16, v26
	v_lshlrev_b32_e32 v56, 16, v6
	v_pk_mul_f32 v[4:5], v[58:59], v[58:59]
	v_pk_fma_f32 v[2:3], v[46:47], v[46:47], v[2:3]
	v_and_b32_e32 v54, 0xffff0000, v25
	v_lshlrev_b32_e32 v61, 16, v27
	v_lshlrev_b32_e32 v60, 16, v7
	v_pk_fma_f32 v[4:5], v[56:57], v[56:57], v[4:5]
	v_pk_fma_f32 v[2:3], v[50:51], v[50:51], v[2:3]
	v_and_b32_e32 v63, 0xffff0000, v27
	v_and_b32_e32 v62, 0xffff0000, v7
	v_pk_fma_f32 v[4:5], v[60:61], v[60:61], v[4:5]
	v_pk_fma_f32 v[2:3], v[54:55], v[54:55], v[2:3]
	v_pk_fma_f32 v[4:5], v[62:63], v[62:63], v[4:5]
	v_add_f32_e32 v1, v2, v3
	v_add_f32_e32 v1, v1, v4
	v_add_f32_e32 v1, v1, v5
	ds_bpermute_b32 v2, v213, v1
	v_add_u32_e32 v24, s67, v0
	v_cmp_lt_i32_e32 vcc, s9, v24
	v_mov_b32_e32 v68, v46
	v_mov_b32_e32 v69, v48
	s_waitcnt lgkmcnt(0)
	v_add_f32_e32 v1, v1, v2
	ds_bpermute_b32 v2, v214, v1
	v_cndmask_b32_e32 v0, v24, v0, vcc
	v_mov_b32_e32 v48, v47
	s_waitcnt lgkmcnt(0)
	v_add_f32_e32 v1, v1, v2
	ds_bpermute_b32 v2, v215, v1
	s_waitcnt lgkmcnt(0)
	v_add_f32_e32 v4, v1, v2
	ds_bpermute_b32 v5, v216, v4
	v_ashrrev_i32_e32 v1, 31, v0
	v_lshlrev_b64 v[2:3], 12, v[0:1]
	v_lshlrev_b64 v[0:1], 11, v[0:1]
	v_lshl_add_u64 v[64:65], v[22:23], 0, v[2:3]
	s_waitcnt lgkmcnt(0)
	v_add_f32_e32 v25, v4, v5
	ds_bpermute_b32 v26, v217, v25
	v_lshl_add_u64 v[66:67], v[18:19], 0, v[0:1]
	global_load_dwordx4 v[4:7], v[64:65], off
	global_load_dwordx4 v[0:3], v[64:65], off offset:1024
	s_waitcnt lgkmcnt(0)
	v_add_f32_e32 v25, v25, v26
	ds_bpermute_b32 v35, v218, v25
	global_load_dwordx2 v[30:31], v[66:67], off
	global_load_dwordx2 v[32:33], v[66:67], off offset:512
	global_load_dwordx2 v[26:27], v[66:67], off offset:1024
	global_load_dwordx2 v[28:29], v[66:67], off offset:1536
	v_mov_b32_e32 v66, v50
	v_mov_b32_e32 v67, v54
	v_mov_b32_e32 v54, v51
	s_waitcnt lgkmcnt(0)
	v_add_f32_e32 v25, v25, v35
	v_fmamk_f32 v25, v25, 0x3a800000, v34
	v_mul_f32_e32 v35, 0x4b800000, v25
	v_cmp_gt_f32_e32 vcc, s10, v25
	s_nop 1
	v_cndmask_b32_e32 v25, v25, v35, vcc
	v_rsq_f32_e32 v25, v25
	s_nop 0
	v_mul_f32_e32 v35, 0x45800000, v25
	v_cndmask_b32_e32 v70, v25, v35, vcc
	v_pk_mul_f32 v[66:67], v[66:67], v[70:71] op_sel_hi:[1,0]
	v_pk_mul_f32 v[68:69], v[68:69], v[70:71] op_sel_hi:[1,0]
	v_pk_mul_f32 v[10:11], v[10:11], v[66:67]
	v_pk_mul_f32 v[8:9], v[8:9], v[68:69]
	v_pk_fma_f32 v[10:11], v[38:39], v[10:11], v[14:15]
	v_pk_fma_f32 v[8:9], v[36:37], v[8:9], v[12:13]
	global_store_dwordx4 v[52:53], v[8:11], off nt
	global_load_dwordx4 v[8:11], v[20:21], off offset:1024
	v_lshl_add_u64 v[66:67], v[44:45], 0, s[4:5]
	global_load_dwordx4 v[12:15], v[66:67], off offset:1024
	v_pk_mul_f32 v[36:37], v[48:49], v[70:71] op_sel_hi:[1,0]
	v_pk_mul_f32 v[38:39], v[54:55], v[70:71] op_sel_hi:[1,0]
	v_mov_b32_e32 v54, v56
	v_mov_b32_e32 v55, v58
	v_pk_mul_f32 v[54:55], v[54:55], v[70:71] op_sel_hi:[1,0]
	v_mov_b32_e32 v58, v57
	v_cmp_gt_i32_e32 vcc, s8, v24
	s_waitcnt vmcnt(1)
	v_pk_mul_f32 v[10:11], v[10:11], v[38:39]
	v_pk_mul_f32 v[8:9], v[8:9], v[36:37]
	s_waitcnt vmcnt(0)
	v_pk_fma_f32 v[10:11], v[14:15], v[10:11], v[42:43]
	v_pk_fma_f32 v[8:9], v[12:13], v[8:9], v[40:41]
	global_store_dwordx4 v[52:53], v[8:11], off offset:1024 nt
	global_load_dwordx4 v[36:39], v[20:21], off offset:2048
	global_load_dwordx4 v[40:43], v[66:67], off offset:2048
	global_load_dwordx4 v[44:47], v[52:53], off offset:2048
	global_load_dwordx4 v[48:51], v[52:53], off offset:3072
	global_load_dwordx4 v[12:15], v[64:65], off offset:2048
	global_load_dwordx4 v[8:11], v[64:65], off offset:3072
	v_mov_b32_e32 v64, v60
	v_mov_b32_e32 v65, v62
	v_pk_mul_f32 v[64:65], v[64:65], v[70:71] op_sel_hi:[1,0]
	v_mov_b32_e32 v62, v61
	s_waitcnt vmcnt(5)
	v_pk_mul_f32 v[38:39], v[38:39], v[64:65]
	v_pk_mul_f32 v[36:37], v[36:37], v[54:55]
	s_waitcnt vmcnt(3)
	v_pk_fma_f32 v[38:39], v[42:43], v[38:39], v[46:47]
	v_pk_fma_f32 v[36:37], v[40:41], v[36:37], v[44:45]
	global_store_dwordx4 v[52:53], v[36:39], off offset:2048 nt
	global_load_dwordx4 v[36:39], v[20:21], off offset:3072
	s_nop 0
	global_load_dwordx4 v[40:43], v[66:67], off offset:3072
	v_pk_mul_f32 v[44:45], v[58:59], v[70:71] op_sel_hi:[1,0]
	v_pk_mul_f32 v[46:47], v[62:63], v[70:71] op_sel_hi:[1,0]
	s_waitcnt vmcnt(1)
	v_pk_mul_f32 v[36:37], v[36:37], v[44:45]
	v_pk_mul_f32 v[38:39], v[38:39], v[46:47]
	s_waitcnt vmcnt(0)
	v_pk_fma_f32 v[36:37], v[40:41], v[36:37], v[48:49]
	v_pk_fma_f32 v[38:39], v[42:43], v[38:39], v[50:51]
	global_store_dwordx4 v[52:53], v[36:39], off offset:3072 nt
	s_and_saveexec_b64 s[6:7], vcc
	s_cbranch_execz .LBB0_1151
	v_add_u32_e32 v25, 0xffffe000, v24
	v_ashrrev_i32_e32 v25, 12, v25
	v_add_u32_e32 v25, 10, v25
	v_cmp_lt_i32_e32 vcc, s11, v24
	v_and_b32_e32 v49, 0xffff0000, v32
	v_and_b32_e32 v48, 0xffff0000, v30
	v_cndmask_b32_e32 v25, 9, v25, vcc
	v_mul_hi_i32_i24_e32 v37, 0x3000, v25
	v_mul_i32_i24_e32 v36, 0x3000, v25
	v_lshl_add_u64 v[36:37], s[0:1], 0, v[36:37]
	v_lshl_add_u64 v[44:45], v[36:37], 0, v[16:17]
	v_add_co_u32_e32 v40, vcc, s12, v44
	global_load_dwordx4 v[36:39], v[20:21], off
	s_nop 0
	v_addc_co_u32_e32 v41, vcc, 0, v45, vcc
	global_load_dwordx4 v[40:43], v[40:41], off
	v_lshlrev_b32_e32 v47, 16, v32
	v_lshlrev_b32_e32 v46, 16, v30
	v_lshlrev_b32_e32 v50, 16, v31
	v_and_b32_e32 v32, 0xffff0000, v31
	v_pk_mul_f32 v[30:31], v[48:49], v[48:49]
	v_and_b32_e32 v55, 0xffff0000, v28
	v_and_b32_e32 v54, 0xffff0000, v26
	v_lshlrev_b32_e32 v51, 16, v33
	v_pk_fma_f32 v[30:31], v[46:47], v[46:47], v[30:31]
	v_lshlrev_b32_e32 v53, 16, v28
	v_lshlrev_b32_e32 v52, 16, v26
	v_lshlrev_b32_e32 v56, 16, v27
	v_and_b32_e32 v58, 0xffff0000, v27
	v_pk_mul_f32 v[26:27], v[54:55], v[54:55]
	v_and_b32_e32 v33, 0xffff0000, v33
	v_pk_fma_f32 v[30:31], v[50:51], v[50:51], v[30:31]
	v_lshlrev_b32_e32 v57, 16, v29
	v_pk_fma_f32 v[26:27], v[52:53], v[52:53], v[26:27]
	v_pk_fma_f32 v[30:31], v[32:33], v[32:33], v[30:31]
	v_and_b32_e32 v59, 0xffff0000, v29
	v_pk_fma_f32 v[26:27], v[56:57], v[56:57], v[26:27]
	v_add_f32_e32 v25, v30, v31
	v_pk_fma_f32 v[26:27], v[58:59], v[58:59], v[26:27]
	v_mov_b32_e32 v28, v50
	v_add_f32_e32 v25, v25, v26
	v_add_f32_e32 v25, v25, v27
	ds_bpermute_b32 v26, v213, v25
	v_mov_b32_e32 v29, v32
	v_mov_b32_e32 v32, v51
	s_waitcnt lgkmcnt(0)
	v_add_f32_e32 v25, v25, v26
	ds_bpermute_b32 v26, v214, v25
	s_waitcnt lgkmcnt(0)
	v_add_f32_e32 v25, v25, v26
	ds_bpermute_b32 v26, v215, v25
	s_waitcnt lgkmcnt(0)
	v_add_f32_e32 v25, v25, v26
	ds_bpermute_b32 v26, v216, v25
	s_waitcnt lgkmcnt(0)
	v_add_f32_e32 v25, v25, v26
	ds_bpermute_b32 v26, v217, v25
	s_waitcnt lgkmcnt(0)
	v_add_f32_e32 v30, v25, v26
	ds_bpermute_b32 v31, v218, v30
	v_ashrrev_i32_e32 v25, 31, v24
	v_lshlrev_b64 v[26:27], 12, v[24:25]
	v_lshl_add_u64 v[60:61], v[22:23], 0, v[26:27]
	s_waitcnt lgkmcnt(0)
	v_add_f32_e32 v25, v30, v31
	v_fmamk_f32 v25, v25, 0x3a800000, v34
	v_mul_f32_e32 v30, 0x4b800000, v25
	v_cmp_gt_f32_e32 vcc, s10, v25
	v_mov_b32_e32 v31, v48
	v_mov_b32_e32 v48, v47
	v_cndmask_b32_e32 v25, v25, v30, vcc
	v_rsq_f32_e32 v25, v25
	v_mov_b32_e32 v30, v46
	v_mul_f32_e32 v26, 0x45800000, v25
	v_cndmask_b32_e32 v46, v25, v26, vcc
	v_pk_mul_f32 v[26:27], v[28:29], v[46:47] op_sel_hi:[1,0]
	v_pk_mul_f32 v[28:29], v[30:31], v[46:47] op_sel_hi:[1,0]
	s_waitcnt vmcnt(1)
	v_pk_mul_f32 v[26:27], v[38:39], v[26:27]
	v_pk_mul_f32 v[28:29], v[36:37], v[28:29]
	v_lshl_add_u64 v[30:31], v[44:45], 0, s[4:5]
	s_waitcnt vmcnt(0)
	v_pk_fma_f32 v[6:7], v[42:43], v[26:27], v[6:7]
	v_pk_fma_f32 v[4:5], v[40:41], v[28:29], v[4:5]
	global_store_dwordx4 v[60:61], v[4:7], off nt
	global_load_dwordx4 v[4:7], v[20:21], off offset:1024
	v_pk_mul_f32 v[36:37], v[48:49], v[46:47] op_sel_hi:[1,0]
	global_load_dwordx4 v[26:29], v[30:31], off offset:1024
	v_pk_mul_f32 v[32:33], v[32:33], v[46:47] op_sel_hi:[1,0]
	s_waitcnt vmcnt(1)
	v_pk_mul_f32 v[4:5], v[4:5], v[36:37]
	v_pk_mul_f32 v[6:7], v[6:7], v[32:33]
	s_waitcnt vmcnt(0)
	v_pk_fma_f32 v[0:1], v[26:27], v[4:5], v[0:1]
	v_pk_fma_f32 v[2:3], v[28:29], v[6:7], v[2:3]
	global_store_dwordx4 v[60:61], v[0:3], off offset:1024 nt
	global_load_dwordx4 v[0:3], v[20:21], off offset:2048
	s_nop 0
	global_load_dwordx4 v[4:7], v[30:31], off offset:2048
	v_mov_b32_e32 v26, v52
	v_mov_b32_e32 v27, v54
	v_mov_b32_e32 v28, v56
	v_mov_b32_e32 v29, v58
	v_pk_mul_f32 v[26:27], v[26:27], v[46:47] op_sel_hi:[1,0]
	v_pk_mul_f32 v[28:29], v[28:29], v[46:47] op_sel_hi:[1,0]
	v_mov_b32_e32 v54, v53
	v_mov_b32_e32 v58, v57
	s_waitcnt vmcnt(1)
	v_pk_mul_f32 v[2:3], v[2:3], v[28:29]
	v_pk_mul_f32 v[0:1], v[0:1], v[26:27]
	s_waitcnt vmcnt(0)
	v_pk_fma_f32 v[2:3], v[6:7], v[2:3], v[14:15]
	v_pk_fma_f32 v[0:1], v[4:5], v[0:1], v[12:13]
	global_store_dwordx4 v[60:61], v[0:3], off offset:2048 nt
	global_load_dwordx4 v[0:3], v[20:21], off offset:3072
	s_nop 0
	global_load_dwordx4 v[4:7], v[30:31], off offset:3072
	v_pk_mul_f32 v[12:13], v[54:55], v[46:47] op_sel_hi:[1,0]
	v_pk_mul_f32 v[14:15], v[58:59], v[46:47] op_sel_hi:[1,0]
	s_waitcnt vmcnt(1)
	v_pk_mul_f32 v[0:1], v[0:1], v[12:13]
	v_pk_mul_f32 v[2:3], v[2:3], v[14:15]
	s_waitcnt vmcnt(0)
	v_pk_fma_f32 v[0:1], v[4:5], v[0:1], v[8:9]
	v_pk_fma_f32 v[2:3], v[6:7], v[2:3], v[10:11]
	global_store_dwordx4 v[60:61], v[0:3], off offset:3072 nt
	s_branch .LBB0_1151
